# final-norm epilogue: second residual batch requested with the first, counted vmcnt(8) wait (prologue/epilogue de-serialisation)
# speedup vs baseline: 1.0079x; 1.0079x over previous
.LBB0_941:
	v_mbcnt_lo_u32_b32 v184, -1, 0
	v_mbcnt_hi_u32_b32 v184, -1, v184
	s_lshl_b32 s9, s34, 8
	v_ashrrev_i32_e32 v183, 3, v184
	v_add_u32_e32 v182, s60, v183
	v_add_u32_e32 v128, s9, v182
	v_ashrrev_i32_e32 v129, 31, v128
	s_lshl_b32 s36, s8, 8
	v_lshlrev_b64 v[128:129], 10, v[128:129]
	s_ashr_i32 s37, s36, 31
	v_lshl_add_u64 v[168:169], v[128:129], 0, s[36:37]
	v_or_b32_e32 v168, s66, v168
	v_lshlrev_b32_e32 v128, 4, v184
	v_and_b32_e32 v156, 0x70, v128
	v_lshl_add_u64 v[128:129], v[168:169], 1, s[12:13]
	v_lshl_add_u64 v[170:171], v[128:129], 0, v[156:157]
	v_add_co_u32_e32 v128, vcc, s55, v170
	v_mul_lo_u32 v183, v183, s71
	s_nop 0
	v_addc_co_u32_e32 v129, vcc, 0, v171, vcc
	global_load_dwordx4 v[186:189], v[170:171], off nt
	global_load_dwordx4 v[190:193], v[128:129], off nt
	v_add_co_u32_e32 v128, vcc, s64, v170
	v_add_u32_e32 v183, s70, v183
	s_nop 0
	v_addc_co_u32_e32 v129, vcc, 0, v171, vcc
	v_add_co_u32_e32 v130, vcc, s74, v170
	v_add_u32_e32 v183, v183, v156
	s_nop 0
	v_addc_co_u32_e32 v131, vcc, 0, v171, vcc
	v_add_co_u32_e32 v132, vcc, s53, v170
	v_add_u32_e32 v185, v174, v172
	s_nop 0
	v_addc_co_u32_e32 v133, vcc, 0, v171, vcc
	v_add_co_u32_e32 v134, vcc, s54, v170
	s_nop 1
	v_addc_co_u32_e32 v135, vcc, 0, v171, vcc
	v_add_co_u32_e32 v194, vcc, s63, v170
	s_nop 1
	v_addc_co_u32_e32 v195, vcc, 0, v171, vcc
	v_add_co_u32_e32 v196, vcc, s65, v170
	s_nop 1
	v_addc_co_u32_e32 v197, vcc, 0, v171, vcc
	global_load_dwordx4 v[144:147], v[128:129], off nt
	global_load_dwordx4 v[148:151], v[130:131], off nt
	global_load_dwordx4 v[136:139], v[132:133], off nt
	global_load_dwordx4 v[140:143], v[134:135], off nt
	s_nop 0
	global_load_dwordx4 v[128:131], v[194:195], off nt
	global_load_dwordx4 v[132:135], v[196:197], off nt
	s_mov_b32 s101, 0
	s_mov_b32 s100, 0x40000
	v_lshl_add_u64 v[234:235], v[170:171], 0, s[100:101]
	global_load_dwordx4 v[202:205], v[234:235], off nt
	s_mov_b32 s100, 0x44000
	v_lshl_add_u64 v[234:235], v[170:171], 0, s[100:101]
	global_load_dwordx4 v[206:209], v[234:235], off nt
	s_mov_b32 s100, 0x48000
	v_lshl_add_u64 v[234:235], v[170:171], 0, s[100:101]
	global_load_dwordx4 v[210:213], v[234:235], off nt
	s_mov_b32 s100, 0x4c000
	v_lshl_add_u64 v[234:235], v[170:171], 0, s[100:101]
	global_load_dwordx4 v[214:217], v[234:235], off nt
	s_mov_b32 s100, 0x50000
	v_lshl_add_u64 v[234:235], v[170:171], 0, s[100:101]
	global_load_dwordx4 v[218:221], v[234:235], off nt
	s_mov_b32 s100, 0x54000
	v_lshl_add_u64 v[234:235], v[170:171], 0, s[100:101]
	global_load_dwordx4 v[222:225], v[234:235], off nt
	s_mov_b32 s100, 0x58000
	v_lshl_add_u64 v[234:235], v[170:171], 0, s[100:101]
	global_load_dwordx4 v[226:229], v[234:235], off nt
	s_mov_b32 s100, 0x5c000
	v_lshl_add_u64 v[234:235], v[170:171], 0, s[100:101]
	global_load_dwordx4 v[230:233], v[234:235], off nt
	s_waitcnt vmcnt(8)
	ds_write_b128 v183, v[186:189]
	ds_write_b128 v183, v[190:193] offset:1152
	ds_read_b128 v[186:189], v185
	ds_read_b128 v[190:193], v185 offset:64
	s_waitcnt lgkmcnt(1)
	v_lshlrev_b32_e32 v194, 16, v186
	v_and_b32_e32 v195, 0xffff0000, v186
	v_lshlrev_b32_e32 v186, 16, v187
	v_and_b32_e32 v187, 0xffff0000, v187
	v_lshlrev_b32_e32 v196, 16, v188
	v_and_b32_e32 v197, 0xffff0000, v188
	v_lshlrev_b32_e32 v188, 16, v189
	v_and_b32_e32 v189, 0xffff0000, v189
	s_waitcnt lgkmcnt(0)
	v_lshlrev_b32_e32 v198, 16, v190
	v_and_b32_e32 v199, 0xffff0000, v190
	v_lshlrev_b32_e32 v190, 16, v191
	v_and_b32_e32 v191, 0xffff0000, v191
	v_lshlrev_b32_e32 v200, 16, v192
	v_and_b32_e32 v201, 0xffff0000, v192
	v_lshlrev_b32_e32 v192, 16, v193
	v_and_b32_e32 v193, 0xffff0000, v193
	v_pk_add_f32 v[124:125], v[124:125], v[194:195]
	v_pk_add_f32 v[126:127], v[126:127], v[186:187]
	v_pk_add_f32 v[120:121], v[120:121], v[196:197]
	v_pk_add_f32 v[122:123], v[122:123], v[188:189]
	v_pk_add_f32 v[108:109], v[108:109], v[198:199]
	v_pk_add_f32 v[110:111], v[110:111], v[190:191]
	v_pk_add_f32 v[100:101], v[100:101], v[200:201]
	v_pk_add_f32 v[102:103], v[102:103], v[192:193]
	v_pk_mul_f32 v[186:187], v[124:125], v[124:125]
	v_pk_mul_f32 v[188:189], v[126:127], v[126:127]
	v_pk_mul_f32 v[190:191], v[120:121], v[120:121]
	v_pk_mul_f32 v[192:193], v[122:123], v[122:123]
	v_pk_mul_f32 v[194:195], v[108:109], v[108:109]
	v_pk_mul_f32 v[196:197], v[110:111], v[110:111]
	v_pk_mul_f32 v[198:199], v[100:101], v[100:101]
	v_pk_mul_f32 v[200:201], v[102:103], v[102:103]
	v_add_f32_e32 v198, v198, v199
	v_add_f32_e32 v156, v200, v201
	v_add_f32_e32 v196, v196, v197
	v_add_f32_e32 v194, v194, v195
	v_add_f32_e32 v192, v192, v193
	v_add_f32_e32 v190, v190, v191
	v_add_f32_e32 v188, v188, v189
	v_add_f32_e32 v186, v186, v187
	v_add_f32_e32 v156, v198, v156
	v_add_f32_e32 v187, v194, v196
	v_add_f32_e32 v189, v190, v192
	v_add_f32_e32 v186, v186, v188
	v_add_f32_e32 v156, v187, v156
	v_add_f32_e32 v186, v186, v189
	v_and_b32_e32 v187, 64, v178
	v_add_f32_e32 v186, v186, v156
	v_add_u32_e32 v188, 64, v187
	v_mov_b32_e32 v187, v186
	s_nop 1
	v_permlane16_swap_b32_e32 v186, v187
	s_waitcnt lgkmcnt(0)
	v_add_f32_e32 v187, v186, v187
	v_xor_b32_e32 v186, 32, v178
	v_cmp_lt_i32_e32 vcc, v186, v188
	s_nop 1
	v_cndmask_b32_e32 v186, v178, v186, vcc
	v_lshlrev_b32_e32 v186, 2, v186
	v_mov_b32_e32 v188, v187
	s_nop 1
	v_permlane32_swap_b32_e32 v187, v188
	s_and_saveexec_b64 s[6:7], s[0:1]
	s_cbranch_execz .LBB0_943
	s_waitcnt lgkmcnt(0)
	v_add_f32_e32 v187, v187, v188
	ds_write_b32 v180, v187

.LBB0_949:
	s_or_b64 exec, exec, s[6:7]
	v_add_co_u32_e32 v128, vcc, 0x40000, v170
	s_waitcnt lgkmcnt(0)
	s_nop 0
	v_addc_co_u32_e32 v129, vcc, 0, v171, vcc
	v_add_co_u32_e32 v130, vcc, 0x44000, v170
	s_nop 1
	v_addc_co_u32_e32 v131, vcc, 0, v171, vcc
	s_waitcnt vmcnt(0)
	v_mov_b64_e32 v[188:189], v[202:203]
	v_mov_b64_e32 v[190:191], v[204:205]
	v_mov_b64_e32 v[192:193], v[206:207]
	v_mov_b64_e32 v[194:195], v[208:209]
	v_add_co_u32_e32 v128, vcc, 0x48000, v170
	s_nop 1
	v_addc_co_u32_e32 v129, vcc, 0, v171, vcc
	v_add_co_u32_e32 v130, vcc, 0x4c000, v170
	s_nop 1
	v_addc_co_u32_e32 v131, vcc, 0, v171, vcc
	v_add_co_u32_e32 v132, vcc, 0x50000, v170
	v_mov_b64_e32 v[144:145], v[210:211]
	v_mov_b64_e32 v[146:147], v[212:213]
	v_mov_b64_e32 v[148:149], v[214:215]
	v_mov_b64_e32 v[150:151], v[216:217]
	v_addc_co_u32_e32 v133, vcc, 0, v171, vcc
	v_add_co_u32_e32 v128, vcc, 0x54000, v170
	s_nop 1
	v_addc_co_u32_e32 v129, vcc, 0, v171, vcc
	v_add_co_u32_e32 v130, vcc, 0x58000, v170
	v_mov_b64_e32 v[136:137], v[218:219]
	v_mov_b64_e32 v[138:139], v[220:221]
	v_mov_b64_e32 v[140:141], v[222:223]
	v_mov_b64_e32 v[142:143], v[224:225]
	v_addc_co_u32_e32 v131, vcc, 0, v171, vcc
	v_add_co_u32_e32 v132, vcc, 0x5c000, v170
	s_nop 1
	v_addc_co_u32_e32 v133, vcc, 0, v171, vcc
	v_mov_b64_e32 v[128:129], v[226:227]
	v_mov_b64_e32 v[130:131], v[228:229]
	s_nop 0
	v_mov_b64_e32 v[132:133], v[230:231]
	v_mov_b64_e32 v[134:135], v[232:233]
	s_waitcnt vmcnt(7)
	ds_write_b128 v183, v[188:191]
	s_waitcnt vmcnt(6)
	ds_write_b128 v183, v[192:195] offset:1152
	ds_read_b128 v[188:191], v185
	ds_read_b128 v[192:195], v185 offset:64
	s_waitcnt lgkmcnt(1)
	v_lshlrev_b32_e32 v170, 16, v188
	v_and_b32_e32 v171, 0xffff0000, v188
	v_lshlrev_b32_e32 v188, 16, v189
	v_and_b32_e32 v189, 0xffff0000, v189
	v_lshlrev_b32_e32 v196, 16, v190
	v_and_b32_e32 v197, 0xffff0000, v190
	v_lshlrev_b32_e32 v190, 16, v191
	v_and_b32_e32 v191, 0xffff0000, v191
	s_waitcnt lgkmcnt(0)
	v_lshlrev_b32_e32 v198, 16, v192
	v_and_b32_e32 v199, 0xffff0000, v192
	v_lshlrev_b32_e32 v192, 16, v193
	v_and_b32_e32 v193, 0xffff0000, v193
	v_lshlrev_b32_e32 v200, 16, v194
	v_and_b32_e32 v201, 0xffff0000, v194
	v_lshlrev_b32_e32 v194, 16, v195
	v_and_b32_e32 v195, 0xffff0000, v195
	v_pk_add_f32 v[60:61], v[60:61], v[170:171]
	v_pk_add_f32 v[62:63], v[62:63], v[188:189]
	v_pk_add_f32 v[56:57], v[56:57], v[196:197]
	v_pk_add_f32 v[58:59], v[58:59], v[190:191]
	v_pk_add_f32 v[52:53], v[52:53], v[198:199]
	v_pk_add_f32 v[54:55], v[54:55], v[192:193]
	v_pk_add_f32 v[48:49], v[48:49], v[200:201]
	v_pk_add_f32 v[50:51], v[50:51], v[194:195]
	v_pk_mul_f32 v[170:171], v[60:61], v[60:61]
	v_pk_mul_f32 v[188:189], v[62:63], v[62:63]
	v_pk_mul_f32 v[190:191], v[56:57], v[56:57]
	v_pk_mul_f32 v[192:193], v[58:59], v[58:59]
	v_pk_mul_f32 v[194:195], v[52:53], v[52:53]
	v_pk_mul_f32 v[196:197], v[54:55], v[54:55]
	v_pk_mul_f32 v[198:199], v[48:49], v[48:49]
	v_pk_mul_f32 v[200:201], v[50:51], v[50:51]
	v_add_f32_e32 v198, v198, v199
	v_add_f32_e32 v187, v200, v201
	v_add_f32_e32 v196, v196, v197
	v_add_f32_e32 v194, v194, v195
	v_add_f32_e32 v192, v192, v193
	v_add_f32_e32 v190, v190, v191
	v_add_f32_e32 v188, v188, v189
	v_add_f32_e32 v170, v170, v171
	v_add_f32_e32 v187, v198, v187
	v_add_f32_e32 v191, v194, v196
	v_add_f32_e32 v190, v190, v192
	v_add_f32_e32 v170, v170, v188
	v_add_f32_e32 v187, v191, v187
	v_add_f32_e32 v170, v170, v190
	v_add_f32_e32 v170, v170, v187
	v_mov_b32_e32 v171, v170
	s_nop 1
	v_permlane16_swap_b32_e32 v170, v171
	s_waitcnt lgkmcnt(0)
	v_add_f32_e32 v170, v170, v171
	v_mov_b32_e32 v171, v170
	s_nop 1
	v_permlane32_swap_b32_e32 v170, v171
	s_and_saveexec_b64 s[6:7], s[0:1]
	s_cbranch_execz .LBB0_951
	s_waitcnt lgkmcnt(0)
	v_add_f32_e32 v170, v170, v171
	ds_write_b32 v180, v170 offset:2048
